# P2 (lora prep): all 32 row loads of a wave issued up front, per-iteration counted waits (was one full memory latency per row, 16 rows serial)
# speedup vs baseline: 1.0112x; 1.0008x over previous
.LBB0_213:
	s_cmp_lt_i32 s84, 3
	s_cselect_b64 s[4:5], -1, 0
	s_and_b64 s[6:7], s[4:5], s[0:1]
	s_andn2_b64 vcc, exec, s[6:7]
	s_cbranch_vccnz .LBB0_273
	s_cmpk_gt_i32 s72, 0x7fff
	s_movk_i32 s14, 0x7fff
	s_cbranch_scc1 .LBB0_273
	v_mov_b32_e32 v7, 0
	v_lshlrev_b32_e32 v6, 3, v152
	v_readlane_b32 s16, v239, 10
	v_lshl_add_u64 v[8:9], s[70:71], 0, v[6:7]
	v_lshlrev_b32_e32 v6, 4, v152
	v_readlane_b32 s20, v239, 14
	v_readlane_b32 s21, v239, 15
	s_add_u32 s15, s78, 0xf000000
	s_addc_u32 s16, s79, 0
	v_lshl_add_u64 v[2:3], s[20:21], 0, v[6:7]
	v_add_co_u32_e32 v2, vcc, 0x3000, v2
	v_lshlrev_b32_e32 v6, 2, v152
	s_nop 0
	v_addc_co_u32_e32 v3, vcc, 0, v3, vcc
	global_load_dwordx4 v[2:5], v[2:3], off
	v_cmp_lt_u32_e64 s[0:1], 15, v152
	v_cmp_lt_u32_e64 s[4:5], 31, v152
	v_lshlrev_b32_e32 v6, 1, v6
	v_mov_b32_e32 v1, 1
	s_mov_b32 s8, s72
	v_readlane_b32 s17, v239, 11
	v_readlane_b32 s18, v239, 12
	v_readlane_b32 s19, v239, 13
	v_readlane_b32 s22, v239, 16
	v_readlane_b32 s23, v239, 17
	v_readlane_b32 s24, v239, 18
	v_readlane_b32 s25, v239, 19
	v_readlane_b32 s26, v239, 20
	v_readlane_b32 s27, v239, 21
	v_readlane_b32 s28, v239, 22
	v_readlane_b32 s29, v239, 23
	v_readlane_b32 s30, v239, 24
	v_readlane_b32 s31, v239, 25
	s_mul_i32 s10, s72, 0x1a00
	s_mul_hi_i32 s11, s72, 0x1a00
	s_add_u32 s10, s15, s10
	s_addc_u32 s11, s16, s11
	s_add_u32 s10, s10, 0x1000
	s_addc_u32 s11, s11, 0
	v_lshl_add_u64 v[92:93], s[10:11], 0, v[6:7]
	global_load_dwordx2 v[20:21], v[92:93], off offset:2048
	v_add_co_u32_e32 v94, vcc, 0xffffe600, v92
	s_nop 1
	v_addc_co_u32_e32 v95, vcc, -1, v93, vcc
	global_load_dwordx2 v[22:23], v[94:95], off offset:2048
	s_add_u32 s10, s10, 0xd00000
	s_addc_u32 s11, s11, 0
	v_lshl_add_u64 v[92:93], s[10:11], 0, v[6:7]
	global_load_dwordx2 v[24:25], v[92:93], off offset:2048
	v_add_co_u32_e32 v94, vcc, 0xffffe600, v92
	s_nop 1
	v_addc_co_u32_e32 v95, vcc, -1, v93, vcc
	global_load_dwordx2 v[26:27], v[94:95], off offset:2048
	s_add_u32 s10, s10, 0xd00000
	s_addc_u32 s11, s11, 0
	v_lshl_add_u64 v[92:93], s[10:11], 0, v[6:7]
	global_load_dwordx2 v[28:29], v[92:93], off offset:2048
	v_add_co_u32_e32 v94, vcc, 0xffffe600, v92
	s_nop 1
	v_addc_co_u32_e32 v95, vcc, -1, v93, vcc
	global_load_dwordx2 v[30:31], v[94:95], off offset:2048
	s_add_u32 s10, s10, 0xd00000
	s_addc_u32 s11, s11, 0
	v_lshl_add_u64 v[92:93], s[10:11], 0, v[6:7]
	global_load_dwordx2 v[32:33], v[92:93], off offset:2048
	v_add_co_u32_e32 v94, vcc, 0xffffe600, v92
	s_nop 1
	v_addc_co_u32_e32 v95, vcc, -1, v93, vcc
	global_load_dwordx2 v[34:35], v[94:95], off offset:2048
	s_add_u32 s10, s10, 0xd00000
	s_addc_u32 s11, s11, 0
	v_lshl_add_u64 v[92:93], s[10:11], 0, v[6:7]
	global_load_dwordx2 v[36:37], v[92:93], off offset:2048
	v_add_co_u32_e32 v94, vcc, 0xffffe600, v92
	s_nop 1
	v_addc_co_u32_e32 v95, vcc, -1, v93, vcc
	global_load_dwordx2 v[38:39], v[94:95], off offset:2048
	s_add_u32 s10, s10, 0xd00000
	s_addc_u32 s11, s11, 0
	v_lshl_add_u64 v[92:93], s[10:11], 0, v[6:7]
	global_load_dwordx2 v[40:41], v[92:93], off offset:2048
	v_add_co_u32_e32 v94, vcc, 0xffffe600, v92
	s_nop 1
	v_addc_co_u32_e32 v95, vcc, -1, v93, vcc
	global_load_dwordx2 v[42:43], v[94:95], off offset:2048
	s_add_u32 s10, s10, 0xd00000
	s_addc_u32 s11, s11, 0
	v_lshl_add_u64 v[92:93], s[10:11], 0, v[6:7]
	global_load_dwordx2 v[44:45], v[92:93], off offset:2048
	v_add_co_u32_e32 v94, vcc, 0xffffe600, v92
	s_nop 1
	v_addc_co_u32_e32 v95, vcc, -1, v93, vcc
	global_load_dwordx2 v[46:47], v[94:95], off offset:2048
	s_add_u32 s10, s10, 0xd00000
	s_addc_u32 s11, s11, 0
	v_lshl_add_u64 v[92:93], s[10:11], 0, v[6:7]
	global_load_dwordx2 v[48:49], v[92:93], off offset:2048
	v_add_co_u32_e32 v94, vcc, 0xffffe600, v92
	s_nop 1
	v_addc_co_u32_e32 v95, vcc, -1, v93, vcc
	global_load_dwordx2 v[50:51], v[94:95], off offset:2048
	s_add_u32 s10, s10, 0xd00000
	s_addc_u32 s11, s11, 0
	v_lshl_add_u64 v[92:93], s[10:11], 0, v[6:7]
	global_load_dwordx2 v[52:53], v[92:93], off offset:2048
	v_add_co_u32_e32 v94, vcc, 0xffffe600, v92
	s_nop 1
	v_addc_co_u32_e32 v95, vcc, -1, v93, vcc
	global_load_dwordx2 v[54:55], v[94:95], off offset:2048
	s_add_u32 s10, s10, 0xd00000
	s_addc_u32 s11, s11, 0
	v_lshl_add_u64 v[92:93], s[10:11], 0, v[6:7]
	global_load_dwordx2 v[56:57], v[92:93], off offset:2048
	v_add_co_u32_e32 v94, vcc, 0xffffe600, v92
	s_nop 1
	v_addc_co_u32_e32 v95, vcc, -1, v93, vcc
	global_load_dwordx2 v[58:59], v[94:95], off offset:2048
	s_add_u32 s10, s10, 0xd00000
	s_addc_u32 s11, s11, 0
	v_lshl_add_u64 v[92:93], s[10:11], 0, v[6:7]
	global_load_dwordx2 v[60:61], v[92:93], off offset:2048
	v_add_co_u32_e32 v94, vcc, 0xffffe600, v92
	s_nop 1
	v_addc_co_u32_e32 v95, vcc, -1, v93, vcc
	global_load_dwordx2 v[62:63], v[94:95], off offset:2048
	s_add_u32 s10, s10, 0xd00000
	s_addc_u32 s11, s11, 0
	v_lshl_add_u64 v[92:93], s[10:11], 0, v[6:7]
	global_load_dwordx2 v[64:65], v[92:93], off offset:2048
	v_add_co_u32_e32 v94, vcc, 0xffffe600, v92
	s_nop 1
	v_addc_co_u32_e32 v95, vcc, -1, v93, vcc
	global_load_dwordx2 v[66:67], v[94:95], off offset:2048
	s_add_u32 s10, s10, 0xd00000
	s_addc_u32 s11, s11, 0
	v_lshl_add_u64 v[92:93], s[10:11], 0, v[6:7]
	global_load_dwordx2 v[68:69], v[92:93], off offset:2048
	v_add_co_u32_e32 v94, vcc, 0xffffe600, v92
	s_nop 1
	v_addc_co_u32_e32 v95, vcc, -1, v93, vcc
	global_load_dwordx2 v[70:71], v[94:95], off offset:2048
	s_add_u32 s10, s10, 0xd00000
	s_addc_u32 s11, s11, 0
	v_lshl_add_u64 v[92:93], s[10:11], 0, v[6:7]
	global_load_dwordx2 v[72:73], v[92:93], off offset:2048
	v_add_co_u32_e32 v94, vcc, 0xffffe600, v92
	s_nop 1
	v_addc_co_u32_e32 v95, vcc, -1, v93, vcc
	global_load_dwordx2 v[74:75], v[94:95], off offset:2048
	s_add_u32 s10, s10, 0xd00000
	s_addc_u32 s11, s11, 0
	v_lshl_add_u64 v[92:93], s[10:11], 0, v[6:7]
	global_load_dwordx2 v[76:77], v[92:93], off offset:2048
	v_add_co_u32_e32 v94, vcc, 0xffffe600, v92
	s_nop 1
	v_addc_co_u32_e32 v95, vcc, -1, v93, vcc
	global_load_dwordx2 v[78:79], v[94:95], off offset:2048
	s_add_u32 s10, s10, 0xd00000
	s_addc_u32 s11, s11, 0
	v_lshl_add_u64 v[92:93], s[10:11], 0, v[6:7]
	global_load_dwordx2 v[80:81], v[92:93], off offset:2048
	v_add_co_u32_e32 v94, vcc, 0xffffe600, v92
	s_nop 1
	v_addc_co_u32_e32 v95, vcc, -1, v93, vcc
	global_load_dwordx2 v[82:83], v[94:95], off offset:2048
	s_branch .LBB0_218

.LBB0_218:
	s_sub_i32 s10, s8, s72
	s_lshr_b32 s10, s10, 12
	s_cmp_lg_u32 s10, 0
	s_cbranch_scc1 .Lp2_n0
	s_waitcnt vmcnt(28)
	v_mov_b32_e32 v84, v20
	v_mov_b32_e32 v85, v21
	v_mov_b32_e32 v86, v22
	v_mov_b32_e32 v87, v23
	v_mov_b32_e32 v88, v24
	v_mov_b32_e32 v89, v25
	v_mov_b32_e32 v90, v26
	v_mov_b32_e32 v91, v27
	s_branch .Lp2_go
.Lp2_n0:
	s_cmp_lg_u32 s10, 1
	s_cbranch_scc1 .Lp2_n1
	s_waitcnt vmcnt(26)
	v_mov_b32_e32 v84, v28
	v_mov_b32_e32 v85, v29
	v_mov_b32_e32 v86, v30
	v_mov_b32_e32 v87, v31
	v_mov_b32_e32 v88, v32
	v_mov_b32_e32 v89, v33
	v_mov_b32_e32 v90, v34
	v_mov_b32_e32 v91, v35
	s_branch .Lp2_go
.Lp2_n1:
	s_cmp_lg_u32 s10, 2
	s_cbranch_scc1 .Lp2_n2
	s_waitcnt vmcnt(24)
	v_mov_b32_e32 v84, v36
	v_mov_b32_e32 v85, v37
	v_mov_b32_e32 v86, v38
	v_mov_b32_e32 v87, v39
	v_mov_b32_e32 v88, v40
	v_mov_b32_e32 v89, v41
	v_mov_b32_e32 v90, v42
	v_mov_b32_e32 v91, v43
	s_branch .Lp2_go
.Lp2_n2:
	s_cmp_lg_u32 s10, 3
	s_cbranch_scc1 .Lp2_n3
	s_waitcnt vmcnt(22)
	v_mov_b32_e32 v84, v44
	v_mov_b32_e32 v85, v45
	v_mov_b32_e32 v86, v46
	v_mov_b32_e32 v87, v47
	v_mov_b32_e32 v88, v48
	v_mov_b32_e32 v89, v49
	v_mov_b32_e32 v90, v50
	v_mov_b32_e32 v91, v51
	s_branch .Lp2_go
.Lp2_n3:
	s_cmp_lg_u32 s10, 4
	s_cbranch_scc1 .Lp2_n4
	s_waitcnt vmcnt(20)
	v_mov_b32_e32 v84, v52
	v_mov_b32_e32 v85, v53
	v_mov_b32_e32 v86, v54
	v_mov_b32_e32 v87, v55
	v_mov_b32_e32 v88, v56
	v_mov_b32_e32 v89, v57
	v_mov_b32_e32 v90, v58
	v_mov_b32_e32 v91, v59
	s_branch .Lp2_go
.Lp2_n4:
	s_cmp_lg_u32 s10, 5
	s_cbranch_scc1 .Lp2_n5
	s_waitcnt vmcnt(18)
	v_mov_b32_e32 v84, v60
	v_mov_b32_e32 v85, v61
	v_mov_b32_e32 v86, v62
	v_mov_b32_e32 v87, v63
	v_mov_b32_e32 v88, v64
	v_mov_b32_e32 v89, v65
	v_mov_b32_e32 v90, v66
	v_mov_b32_e32 v91, v67
	s_branch .Lp2_go
.Lp2_n5:
	s_cmp_lg_u32 s10, 6
	s_cbranch_scc1 .Lp2_n6
	s_waitcnt vmcnt(16)
	v_mov_b32_e32 v84, v68
	v_mov_b32_e32 v85, v69
	v_mov_b32_e32 v86, v70
	v_mov_b32_e32 v87, v71
	v_mov_b32_e32 v88, v72
	v_mov_b32_e32 v89, v73
	v_mov_b32_e32 v90, v74
	v_mov_b32_e32 v91, v75
	s_branch .Lp2_go
.Lp2_n6:
	s_waitcnt vmcnt(14)
	v_mov_b32_e32 v84, v76
	v_mov_b32_e32 v85, v77
	v_mov_b32_e32 v86, v78
	v_mov_b32_e32 v87, v79
	v_mov_b32_e32 v88, v80
	v_mov_b32_e32 v89, v81
	v_mov_b32_e32 v90, v82
	v_mov_b32_e32 v91, v83
.Lp2_go:
	s_and_b32 s12, s8, 0x3fff
	s_ashr_i32 s9, s8, 31
	s_mul_i32 s10, s8, 0x1a00
	s_mul_hi_i32 s11, s8, 0x1a00
	s_add_u32 s10, s15, s10
	s_addc_u32 s11, s16, s11
	v_lshl_add_u64 v[10:11], s[10:11], 0, v[6:7]
	v_add_co_u32_e32 v10, vcc, 0x1000, v10
	s_cmp_eq_u32 s12, 0
	s_nop 0
	v_addc_co_u32_e32 v11, vcc, 0, v11, vcc
	v_mov_b32_e32 v10, v84
	v_mov_b32_e32 v11, v85
	s_cbranch_scc1 .LBB0_220
	s_add_i32 s10, s8, -1
	s_mul_hi_i32 s11, s10, 0x1a00
	s_mulk_i32 s10, 0x1a00
	s_add_u32 s10, s15, s10
	s_addc_u32 s11, s16, s11
	v_lshl_add_u64 v[12:13], s[10:11], 0, v[6:7]
	v_add_co_u32_e32 v12, vcc, 0x1000, v12
	s_nop 1
	v_addc_co_u32_e32 v13, vcc, 0, v13, vcc
	v_mov_b32_e32 v12, v86
	v_mov_b32_e32 v13, v87
	s_branch .LBB0_221

.LBB0_221:
	v_lshlrev_b32_e32 v14, 16, v10
	v_lshlrev_b32_e32 v15, 16, v12
	v_sub_f32_e32 v15, v15, v14
	v_fmac_f32_e32 v14, v2, v15
	s_and_saveexec_b64 s[10:11], s[0:1]
	s_xor_b64 s[10:11], exec, s[10:11]
	s_cbranch_execz .LBB0_225
	s_and_saveexec_b64 s[12:13], s[4:5]
	s_cbranch_execz .LBB0_224
	v_mul_f32_e32 v14, 0xbfb8aa3b, v14
	v_exp_f32_e32 v14, v14
	s_nop 0
	v_add_f32_e32 v14, 1.0, v14
	v_div_scale_f32 v15, s[18:19], v14, v14, 1.0
	v_rcp_f32_e32 v16, v15
	v_div_scale_f32 v17, vcc, 1.0, v14, 1.0
	v_fma_f32 v18, -v15, v16, 1.0
	v_fmac_f32_e32 v16, v18, v16
	v_mul_f32_e32 v18, v17, v16
	v_fma_f32 v19, -v15, v18, v17
	v_fmac_f32_e32 v18, v19, v16
	v_fma_f32 v15, -v15, v18, v17
	v_div_fmas_f32 v15, v15, v16, v18
	v_div_fixup_f32 v14, v15, v14, 1.0

.LBB0_245:
	s_or_b64 exec, exec, s[10:11]
	v_and_b32_sdwa v13, v12, v1 dst_sel:DWORD dst_unused:UNUSED_PAD src0_sel:WORD_1 src1_sel:DWORD
	v_and_b32_sdwa v15, v14, v1 dst_sel:DWORD dst_unused:UNUSED_PAD src0_sel:WORD_1 src1_sel:DWORD
	v_add3_u32 v12, v12, v13, s14
	v_and_b32_sdwa v13, v11, v1 dst_sel:DWORD dst_unused:UNUSED_PAD src0_sel:WORD_1 src1_sel:DWORD
	v_add3_u32 v14, v14, v15, s14
	v_and_b32_sdwa v15, v10, v1 dst_sel:DWORD dst_unused:UNUSED_PAD src0_sel:WORD_1 src1_sel:DWORD
	v_add3_u32 v11, v11, v13, s14
	v_add3_u32 v10, v10, v15, s14
	v_and_b32_e32 v11, 0xffff0000, v11
	s_lshl_b64 s[10:11], s[8:9], 9
	v_and_b32_e32 v10, 0xffff0000, v10
	v_or_b32_sdwa v11, v11, v12 dst_sel:DWORD dst_unused:UNUSED_PAD src0_sel:DWORD src1_sel:WORD_1
	v_lshl_add_u64 v[12:13], v[8:9], 0, s[10:11]
	s_add_i32 s10, s8, s94
	v_or_b32_sdwa v10, v10, v14 dst_sel:DWORD dst_unused:UNUSED_PAD src0_sel:DWORD src1_sel:WORD_1
	s_cmpk_gt_i32 s10, 0x7fff
	s_mov_b64 s[12:13], -1
	global_store_dwordx2 v[12:13], v[10:11], off
	s_cbranch_scc1 .LBB0_217
	s_and_b32 s11, s10, 0x3fff
	s_mul_i32 s8, s10, 0x1a00
	s_mul_hi_i32 s9, s10, 0x1a00
	s_add_u32 s8, s15, s8
	s_addc_u32 s9, s16, s9
	v_lshl_add_u64 v[10:11], s[8:9], 0, v[6:7]
	v_add_co_u32_e32 v10, vcc, 0x1000, v10
	s_cmp_eq_u32 s11, 0
	s_nop 0
	v_addc_co_u32_e32 v11, vcc, 0, v11, vcc
	v_mov_b32_e32 v10, v88
	v_mov_b32_e32 v11, v89
	s_cbranch_scc1 .LBB0_248
	s_add_i32 s8, s10, -1
	s_mul_hi_i32 s9, s8, 0x1a00
	s_mulk_i32 s8, 0x1a00
	s_add_u32 s8, s15, s8
	s_addc_u32 s9, s16, s9
	v_lshl_add_u64 v[12:13], s[8:9], 0, v[6:7]
	v_add_co_u32_e32 v12, vcc, 0x1000, v12
	s_nop 1
	v_addc_co_u32_e32 v13, vcc, 0, v13, vcc
	v_mov_b32_e32 v12, v90
	v_mov_b32_e32 v13, v91
	s_branch .LBB0_249

.LBB0_249:
	v_lshlrev_b32_e32 v14, 16, v10
	v_lshlrev_b32_e32 v15, 16, v12
	v_sub_f32_e32 v15, v15, v14
	v_fmac_f32_e32 v14, v2, v15
	s_and_saveexec_b64 s[8:9], s[0:1]
	s_xor_b64 s[8:9], exec, s[8:9]
	s_cbranch_execz .LBB0_253
	s_and_saveexec_b64 s[12:13], s[4:5]
	s_cbranch_execz .LBB0_252
	v_mul_f32_e32 v14, 0xbfb8aa3b, v14
	v_exp_f32_e32 v14, v14
	s_nop 0
	v_add_f32_e32 v14, 1.0, v14
	v_div_scale_f32 v15, s[18:19], v14, v14, 1.0
	v_rcp_f32_e32 v16, v15
	v_div_scale_f32 v17, vcc, 1.0, v14, 1.0
	v_fma_f32 v18, -v15, v16, 1.0
	v_fmac_f32_e32 v16, v18, v16
	v_mul_f32_e32 v18, v17, v16
	v_fma_f32 v19, -v15, v18, v17
	v_fmac_f32_e32 v18, v19, v16
	v_fma_f32 v15, -v15, v18, v17
	v_div_fmas_f32 v15, v15, v16, v18
	v_div_fixup_f32 v14, v15, v14, 1.0
